# P10: odd workgroups (odd XCDs) start the last GEMM 12us late so epilogue HBM bursts interleave with the other half's mainloop
# baseline (speedup 1.0000x reference)
.LBB0_1182:
	s_cmp_lt_i32 s34, 11
	s_cselect_b64 s[4:5], -1, 0
	s_and_b64 s[0:1], s[4:5], s[0:1]
	s_andn2_b64 vcc, exec, s[0:1]
	s_cbranch_vccnz .LBB0_1207
	s_cmpk_gt_i32 s2, 0x1ff
	v_readfirstlane_b32 s4, v0
	s_cbranch_scc1 .LBB0_1207
	s_bitcmp1_b32 s2, 0
	s_cbranch_scc0 .Lstag_p10_done
	s_memrealtime s[0:1]
	s_waitcnt lgkmcnt(0)
.Lstag_p10_loop:
	s_sleep 8
	s_memrealtime s[6:7]
	s_waitcnt lgkmcnt(0)
	s_sub_u32 s6, s6, s0
	s_cmp_lt_u32 s6, 1200
	s_cbranch_scc1 .Lstag_p10_loop
.Lstag_p10_done:
	s_ashr_i32 s3, s2, 31
	s_lshr_b32 s0, s3, 29
	s_add_i32 s7, s2, s0
	s_and_b32 s0, s7, -8
	s_sub_i32 s5, s2, s0
	s_cmp_gt_i32 s5, -1
	s_cbranch_scc0 .LBB0_1186
	s_lshl_b32 s6, s5, 6
	s_ashr_i32 s0, s7, 3
	s_cbranch_execz .LBB0_1187
	s_branch .LBB0_1188
